# hgrn3: output-gate and norm-weight loads hoisted to job start (tail had 4 serialized load/store round trips)
# baseline (speedup 1.0000x reference)
; __device__ __forceinline__ unsigned pk2(float lo, float hi) { return pg8::cvt_pk_bf16(lo, hi); }
; __device__ __forceinline__ void hgrn3_phase(unsigned char* ws, const float* lbl, const float* nw, LAS unsigned char* lds, int tid, int lane, int wave, int G) {
;     ...
;             const int t = 16 * tt + fr;
;             const float rinv = 1.f / sqrtf((ssq[t] + ssq[64 + t]) * (1.f / 128.f) + RMS_EPS);
; #pragma unroll
;             for (int n = 0; n < 4; ++n) {
;                 const int dv = 16 * (4 * wh + n) + 4 * fq;
;                 const f32x4 nwv = gld<f32x4>(nw + hh * 128 + dv);
;                 const v2u gw_ = gpre[n];
;                 const f32x4 gv = (f32x4){__builtin_bit_cast(float, gw_.x << 16), __builtin_bit_cast(float, gw_.x & 0xffff0000u), __builtin_bit_cast(float, gw_.y << 16), __builtin_bit_cast(float, gw_.y & 0xffff0000u)};
;                 const f32x4 ov = oacc[n] * rinv * nwv * gv;
;                 v2u w; w.x = pk2(ov[0], ov[1]); w.y = pk2(ov[2], ov[3]);
;                 gst<v2u>(MO + (size_t)(tok0 + t) * 1024 + 512 + hh * 128 + dv, w);
;             }
;         }
;         __syncthreads();
.LBB0_23:
	s_or_b64 exec, exec, s[0:1]
	s_waitcnt lgkmcnt(0)
	s_barrier
	ds_read2st64_b32 v[34:35], v115 offset1:1
	v_lshlrev_b32_e32 v50, 16, v214
	v_and_b32_e32 v51, 0xffff0000, v214
	v_lshlrev_b32_e32 v38, 16, v215
	v_and_b32_e32 v39, 0xffff0000, v215
	s_waitcnt lgkmcnt(0)
	v_add_f32_e32 v34, v34, v35
	v_mov_b32_e32 v35, 0x358637bd
	v_fmamk_f32 v34, v34, 0x3c000000, v35
	v_cmp_gt_f32_e32 vcc, s34, v34
	v_mul_f32_e32 v35, 0x4f800000, v34
	s_add_i32 s43, s43, s38
	v_cndmask_b32_e32 v34, v34, v35, vcc
	v_sqrt_f32_e32 v35, v34
	s_add_i32 s42, s42, s41
	v_lshl_add_u64 v[100:101], v[100:101], 0, s[54:55]
	v_add_u32_e32 v36, -1, v35
	v_fma_f32 v37, -v36, v35, v34
	v_cmp_ge_f32_e64 s[0:1], 0, v37
	v_add_u32_e32 v37, 1, v35
	s_nop 0
	v_cndmask_b32_e64 v36, v35, v36, s[0:1]
	v_fma_f32 v35, -v37, v35, v34
	v_cmp_lt_f32_e64 s[0:1], 0, v35
	s_nop 1
	v_cndmask_b32_e64 v35, v36, v37, s[0:1]
	v_mul_f32_e32 v36, 0x37800000, v35
	v_cndmask_b32_e32 v35, v35, v36, vcc
	v_cmp_class_f32_e32 vcc, v34, v204
	s_nop 1
	v_cndmask_b32_e32 v34, v35, v34, vcc
	v_div_scale_f32 v35, s[0:1], v34, v34, 1.0
	v_rcp_f32_e32 v36, v35
	s_mov_b64 s[0:1], 0x7000400
	v_fma_f32 v37, -v35, v36, 1.0
	v_fmac_f32_e32 v36, v37, v36
	v_div_scale_f32 v37, vcc, 1.0, v34, 1.0
	v_mul_f32_e32 v46, v37, v36
	v_fma_f32 v47, -v35, v46, v37
	v_fmac_f32_e32 v46, v47, v36
	v_fma_f32 v35, -v35, v46, v37
	v_div_fmas_f32 v35, v35, v36, v46
	v_lshlrev_b64 v[36:37], 11, v[44:45]
	v_lshl_add_u64 v[36:37], s[68:69], 0, v[36:37]
	v_lshl_add_u64 v[48:49], v[36:37], 0, s[90:91]
	s_lshl_b32 s90, s48, 2
	v_div_fixup_f32 v34, v35, v34, 1.0
	v_pk_mul_f32 v[52:53], v[70:71], v[34:35] op_sel_hi:[1,0]
	v_pk_mul_f32 v[54:55], v[68:69], v[34:35] op_sel_hi:[1,0]
	v_pk_mul_f32 v[42:43], v[42:43], v[34:35] op_sel_hi:[1,0]
	v_pk_mul_f32 v[40:41], v[40:41], v[34:35] op_sel_hi:[1,0]
	v_pk_mul_f32 v[26:27], v[26:27], v[34:35] op_sel_hi:[1,0]
	v_pk_mul_f32 v[24:25], v[24:25], v[34:35] op_sel_hi:[1,0]
	s_mov_b32 s48, s44
	v_pk_mul_f32 v[44:45], v[184:185], v[54:55]
	v_pk_mul_f32 v[46:47], v[186:187], v[52:53]
	v_pk_mul_f32 v[44:45], v[44:45], v[50:51]
	v_pk_mul_f32 v[38:39], v[46:47], v[38:39]
	v_lshl_add_u64 v[46:47], v[96:97], 1, v[48:49]
	v_cvt_pk_bf16_f32 v44, v44, v45
	v_cvt_pk_bf16_f32 v45, v38, v39
	v_lshl_add_u64 v[38:39], v[46:47], 0, s[0:1]
	s_mov_b32 s0, 0x7000000
	v_add_co_u32_e32 v46, vcc, s0, v46
	v_pk_mul_f32 v[50:51], v[58:59], v[34:35] op_sel_hi:[1,0]
	s_nop 0
	v_addc_co_u32_e32 v47, vcc, 0, v47, vcc
	global_store_dwordx2 v[46:47], v[44:45], off offset:1024
	v_pk_mul_f32 v[52:53], v[56:57], v[34:35] op_sel_hi:[1,0]
	v_lshlrev_b32_e32 v48, 16, v216
	v_and_b32_e32 v49, 0xffff0000, v216
	v_lshlrev_b32_e32 v32, 16, v217
	v_and_b32_e32 v33, 0xffff0000, v217
	s_andn2_b64 vcc, exec, s[56:57]
	v_pk_mul_f32 v[44:45], v[188:189], v[52:53]
	v_pk_mul_f32 v[46:47], v[190:191], v[50:51]
	v_pk_mul_f32 v[44:45], v[44:45], v[48:49]
	v_pk_mul_f32 v[32:33], v[46:47], v[32:33]
	v_cvt_pk_bf16_f32 v44, v44, v45
	v_cvt_pk_bf16_f32 v45, v32, v33
	global_store_dwordx2 v[38:39], v[44:45], off offset:32
	v_lshlrev_b32_e32 v32, 16, v218
	v_and_b32_e32 v33, 0xffff0000, v218
	v_lshlrev_b32_e32 v30, 16, v219
	v_and_b32_e32 v31, 0xffff0000, v219
	v_pk_mul_f32 v[40:41], v[192:193], v[40:41]
	v_pk_mul_f32 v[42:43], v[194:195], v[42:43]
	v_pk_mul_f32 v[32:33], v[40:41], v[32:33]
	v_pk_mul_f32 v[30:31], v[42:43], v[30:31]
	v_cvt_pk_bf16_f32 v32, v32, v33
	v_cvt_pk_bf16_f32 v33, v30, v31
	global_store_dwordx2 v[38:39], v[32:33], off offset:64
	v_lshlrev_b32_e32 v36, 16, v220
	v_and_b32_e32 v37, 0xffff0000, v220
	v_lshlrev_b32_e32 v28, 16, v221
	v_and_b32_e32 v29, 0xffff0000, v221
	v_pk_mul_f32 v[24:25], v[196:197], v[24:25]
	v_pk_mul_f32 v[26:27], v[198:199], v[26:27]
	v_pk_mul_f32 v[24:25], v[24:25], v[36:37]
	v_pk_mul_f32 v[26:27], v[26:27], v[28:29]
	v_cvt_pk_bf16_f32 v24, v24, v25
	v_cvt_pk_bf16_f32 v25, v26, v27
	global_store_dwordx2 v[38:39], v[24:25], off offset:96
	s_barrier
	s_cbranch_vccz .LBB0_40
; __device__ __forceinline__ void hgrn3_phase(unsigned char* ws, const float* lbl, const float* nw, LAS unsigned char* lds, int tid, int lane, int wave, int G) {
;     ...
;     for (int job = blockIdx.x; job < 4096; job += G) {
;         int hh, tok0; hg_job(job, hh, tok0);
;         hg_put(rQ, rawQ, tid); hg_put(rF, rawF, tid); hg_put(rI, rawI, tid);
;         bf16x8 sf[4][4];
; #pragma unroll
;         for (int n = 0; n < 4; ++n)
; #pragma unroll
;             for (int kk = 0; kk < 4; ++kk) sf[n][kk] = gld<bf16x8>(DS + (size_t)job * 16384 + ((4 * wh + n) * 4 + kk) * 512 + lane * 8);
;         __syncthreads();
;     ...
;         for (int n = 0; n < 4; ++n) gpre[n] = gld<v2u>(HG + (size_t)(tok0 + 16 * tt + fr) * 512 + hh * 128 + 16 * (4 * wh + n) + 4 * fq);
;     ...
;                 const f32x4 nwv = gld<f32x4>(nw + hh * 128 + dv);
.LBB0_24:
	s_and_b32 s24, s42, 0x1fc0
	s_and_b32 s25, s43, 0xffffe000
	s_or_b32 s24, s25, s24
	s_and_b32 s25, s48, 0x180
	s_lshl_b32 s26, s25, 1
	s_mov_b32 s27, s91
	v_add_u32_e32 v222, s24, v109
	v_readlane_b32 s28, v253, 17
	v_ashrrev_i32_e32 v223, 31, v222
	s_lshl_b32 s28, s28, 1
	s_mov_b32 s29, s91
	v_lshlrev_b64 v[224:225], 10, v[222:223]
	s_lshl_b32 s30, s25, 2
	s_mov_b32 s31, s91
	v_lshl_add_u64 v[224:225], s[2:3], 0, v[224:225]
	v_lshl_add_u64 v[226:227], v[98:99], 0, s[30:31]
	v_lshl_add_u64 v[224:225], v[224:225], 0, s[26:27]
	v_lshl_add_u64 v[224:225], v[94:95], 1, v[224:225]
	v_lshl_add_u64 v[224:225], v[224:225], 0, s[28:29]
	global_load_dwordx4 v[184:187], v[226:227], off
	global_load_dwordx4 v[188:191], v[226:227], off offset:64
	global_load_dwordx4 v[192:195], v[226:227], off offset:128
	global_load_dwordx4 v[196:199], v[226:227], off offset:192
	global_load_dwordx2 v[214:215], v[224:225], off
	global_load_dwordx2 v[216:217], v[224:225], off offset:32
	global_load_dwordx2 v[218:219], v[224:225], off offset:64
	global_load_dwordx2 v[220:221], v[224:225], off offset:96
	v_add_co_u32_e32 v24, vcc, s47, v100
	s_movk_i32 s0, 0x2000
	s_nop 0
	v_addc_co_u32_e32 v25, vcc, 0, v101, vcc
	v_add_co_u32_e32 v26, vcc, s0, v100
	global_load_dwordx4 v[76:79], v[100:101], off
	global_load_dwordx4 v[72:75], v[100:101], off offset:1024
	global_load_dwordx4 v[68:71], v[100:101], off offset:2048
	global_load_dwordx4 v[56:59], v[100:101], off offset:3072
	v_addc_co_u32_e32 v27, vcc, 0, v101, vcc
	v_add_co_u32_e32 v102, vcc, 0x3000, v100
	global_load_dwordx4 v[60:63], v[24:25], off offset:1024
	global_load_dwordx4 v[64:67], v[24:25], off offset:2048
	global_load_dwordx4 v[44:47], v[26:27], off
	global_load_dwordx4 v[48:51], v[26:27], off offset:1024
	global_load_dwordx4 v[52:55], v[26:27], off offset:2048
	global_load_dwordx4 v[40:43], v[26:27], off offset:3072
	v_addc_co_u32_e32 v103, vcc, 0, v101, vcc
	global_load_dwordx4 v[80:83], v[24:25], off offset:3072
	global_load_dwordx4 v[36:39], v[102:103], off
	global_load_dwordx4 v[32:35], v[102:103], off offset:1024
	global_load_dwordx4 v[28:31], v[102:103], off offset:2048
	global_load_dwordx4 v[84:87], v[26:27], off offset:-4096
	s_nop 0
	global_load_dwordx4 v[24:27], v[102:103], off offset:3072
	s_add_i32 s44, s48, s80
	s_cmpk_gt_i32 s44, 0xfff
	s_cselect_b64 s[56:57], -1, 0
	s_and_b64 vcc, exec, s[56:57]
	s_waitcnt vmcnt(29)
	ds_write_b128 v116, v[0:3]
	s_waitcnt vmcnt(28)
	ds_write_b128 v117, v[4:7]
	s_waitcnt vmcnt(27)
	ds_write_b128 v116, v[8:11] offset:17408
	s_waitcnt vmcnt(26)
	ds_write_b128 v117, v[12:15] offset:17408
	s_waitcnt vmcnt(25)
	ds_write_b128 v116, v[16:19] offset:34816
	s_waitcnt vmcnt(24)
	ds_write_b128 v117, v[20:23] offset:34816
	s_waitcnt lgkmcnt(0)
	s_barrier
	s_cbranch_vccnz .LBB0_26
	s_add_i32 s1, s38, s43
	s_add_i32 s49, s41, s42
	s_and_b32 s1, s1, 0xffffe000
	s_and_b32 s49, s49, 0x1fc0
	s_or_b32 s1, s1, s49
	s_and_b32 s0, s44, 0x180
	v_add_u32_e32 v2, s1, v105
	v_add_u32_e32 v4, s1, v106
	s_lshl_b32 s90, s0, 1
	v_ashrrev_i32_e32 v3, 31, v2
	v_ashrrev_i32_e32 v5, 31, v4
	v_lshl_add_u64 v[0:1], v[88:89], 0, s[90:91]
	v_lshlrev_b64 v[16:17], 10, v[2:3]
	v_lshlrev_b64 v[18:19], 10, v[4:5]
	v_lshl_add_u64 v[8:9], v[90:91], 0, s[90:91]
	v_lshl_add_u64 v[20:21], v[92:93], 0, s[90:91]
	v_lshl_add_u64 v[2:3], v[0:1], 0, v[16:17]
	v_lshl_add_u64 v[4:5], v[0:1], 0, v[18:19]
	v_lshl_add_u64 v[10:11], v[8:9], 0, v[16:17]
	v_lshl_add_u64 v[12:13], v[8:9], 0, v[18:19]
	v_lshl_add_u64 v[16:17], v[20:21], 0, v[16:17]
	v_lshl_add_u64 v[20:21], v[20:21], 0, v[18:19]
	global_load_dwordx4 v[0:3], v[2:3], off
	s_nop 0
	global_load_dwordx4 v[4:7], v[4:5], off
	s_nop 0
	global_load_dwordx4 v[8:11], v[10:11], off
	s_nop 0
	global_load_dwordx4 v[12:15], v[12:13], off
	s_nop 0
	global_load_dwordx4 v[16:19], v[16:17], off
	s_nop 0
	global_load_dwordx4 v[20:23], v[20:21], off

; #define LAS __attribute__((address_space(3)))
; __device__ __forceinline__ unsigned pk2(float lo, float hi) { return pg8::cvt_pk_bf16(lo, hi); }
; __device__ __forceinline__ void hg_decay(LAS const unsigned char* rawF, LAS float* part, float lbc, int c, int j, float (&bc)[16], float (&kv)[16], float& tot, float& bref) {
;     ...
;     for (int i = 0; i < 16; ++i) bc[i] += pre;
;     tot = (p0 + p1) + (p2 + p3); bref = p0 + p1;
; __device__ __forceinline__ void hgrn3_phase(unsigned char* ws, const float* lbl, const float* nw, LAS unsigned char* lds, int tid, int lane, int wave, int G) {
;     ...
; #pragma unroll
;             for (int i = 0; i < 16; ++i) {
;                 const int t = 16 * j + i;
;                 const float q = bf2f(*(LAS const unsigned short*)(rawQ + t * RAWP + 2 * c));
;                 const float dq = fminf(fmaxf(bc[i] - bref, -80.f), 80.f);
;                 *(LAS unsigned short*)(QT + t * RAWP + 2 * c) = (unsigned short)pk2(q * __expf(dq), 0.f);
;                 *(LAS unsigned short*)(KT + t * RAWP + 2 * c) = (unsigned short)pk2(kv[i] * __expf(-dq), 0.f);
;                 *(LAS unsigned short*)(QH + t * RAWP + 2 * c) = (unsigned short)pk2(q * __expf(bc[i]), 0.f);
;             }
.LBB0_36:
	s_or_b64 exec, exec, s[0:1]
	v_sub_f32_e32 v164, 1.0, v133
	v_sub_f32_e32 v133, 1.0, v157
	v_add_f32_e32 v157, v129, v161
	v_sub_f32_e32 v162, 1.0, v130
	v_sub_f32_e32 v130, 1.0, v159
	v_add_f32_e32 v159, v134, v161
	v_add_f32_e32 v134, v150, v161
	v_sub_f32_e32 v150, v157, v102
	s_mov_b32 s0, 0xc2a00000
	v_med3_f32 v150, v150, s0, v210
	v_sub_f32_e32 v163, 1.0, v131
	v_sub_f32_e32 v131, 1.0, v158
	v_add_f32_e32 v158, v132, v161
	v_add_f32_e32 v132, v152, v161
	v_mul_f32_e32 v152, 0x3fb8aa3b, v150
	v_exp_f32_e32 v152, v152
	v_sub_f32_e32 v103, 1.0, v160
	v_add_f32_e32 v135, v135, v161
	v_add_f32_e32 v136, v136, v161
	v_add_f32_e32 v137, v137, v161
	v_add_f32_e32 v138, v138, v161
	v_add_f32_e32 v143, v143, v161
	v_add_f32_e32 v144, v144, v161
	v_add_f32_e32 v145, v145, v161
	v_add_f32_e32 v146, v146, v161
	v_add_f32_e32 v147, v147, v161
	v_add_f32_e32 v148, v148, v161
	v_add_f32_e32 v129, v153, v161
	ds_read_u16 v153, v108
	ds_read_u16 v160, v108 offset:272
	ds_read_u16 v161, v108 offset:544
	ds_read_u16 v166, v108 offset:816
	ds_read_u16 v167, v108 offset:1088
	ds_read_u16 v168, v108 offset:1360
	ds_read_u16 v169, v108 offset:1632
	ds_read_u16 v180, v108 offset:1904
	s_waitcnt lgkmcnt(7)
	v_lshlrev_b32_e32 v153, 16, v153
	v_mul_f32_e32 v152, v152, v153
	v_mul_f32_e32 v150, 0xbfb8aa3b, v150
	v_cvt_pk_bf16_f32 v152, v152, s0
	v_exp_f32_e32 v150, v150
	ds_write_b16 v108, v152 offset:52224
	v_mul_f32_e32 v152, 0x3fb8aa3b, v157
	v_exp_f32_e32 v152, v152
	v_mul_f32_e32 v150, v162, v150
	v_cvt_pk_bf16_f32 v150, v150, s0
	ds_write_b16 v119, v150
	v_mul_f32_e32 v150, v152, v153
	v_sub_f32_e32 v152, v158, v102
	v_med3_f32 v152, v152, s0, v210
	v_mul_f32_e32 v153, 0x3fb8aa3b, v152
	v_exp_f32_e32 v153, v153
	v_cvt_pk_bf16_f32 v150, v150, s0
	v_mul_f32_e32 v152, 0xbfb8aa3b, v152
	ds_write_b16 v120, v150
	s_waitcnt lgkmcnt(9)
	v_lshlrev_b32_e32 v150, 16, v160
	v_exp_f32_e32 v152, v152
	v_mul_f32_e32 v153, v153, v150
	v_cvt_pk_bf16_f32 v153, v153, s0
	ds_write_b16 v108, v153 offset:52496
	v_mul_f32_e32 v153, 0x3fb8aa3b, v158
	v_exp_f32_e32 v153, v153
	v_mul_f32_e32 v152, v163, v152
	v_cvt_pk_bf16_f32 v152, v152, s0
	ds_write_b16 v119, v152 offset:272
	v_sub_f32_e32 v152, v159, v102
	v_med3_f32 v152, v152, s0, v210
	v_mul_f32_e32 v150, v153, v150
	v_mul_f32_e32 v153, 0x3fb8aa3b, v152
	v_exp_f32_e32 v153, v153
	v_cvt_pk_bf16_f32 v150, v150, s0
	v_mul_f32_e32 v152, 0xbfb8aa3b, v152
	ds_write_b16 v120, v150 offset:272
	s_waitcnt lgkmcnt(11)
	v_lshlrev_b32_e32 v150, 16, v161
	v_exp_f32_e32 v152, v152
	v_mul_f32_e32 v153, v153, v150
	v_cvt_pk_bf16_f32 v153, v153, s0
	ds_write_b16 v108, v153 offset:52768
	v_mul_f32_e32 v153, 0x3fb8aa3b, v159
	v_exp_f32_e32 v153, v153
	v_mul_f32_e32 v152, v164, v152
	v_cvt_pk_bf16_f32 v152, v152, s0
	ds_write_b16 v119, v152 offset:544
	v_sub_f32_e32 v152, v135, v102
	v_med3_f32 v152, v152, s0, v210
	v_mul_f32_e32 v150, v153, v150
	v_mul_f32_e32 v153, 0x3fb8aa3b, v152
	v_mul_f32_e32 v152, 0xbfb8aa3b, v152
	v_exp_f32_e32 v152, v152
	v_sub_f32_e32 v139, 1.0, v139
	v_mul_f32_e32 v135, 0x3fb8aa3b, v135
	v_exp_f32_e32 v153, v153
	v_exp_f32_e32 v135, v135
	v_mul_f32_e32 v139, v139, v152
	v_cvt_pk_bf16_f32 v139, v139, s0
	v_cvt_pk_bf16_f32 v150, v150, s0
	ds_write_b16 v119, v139 offset:816
	v_sub_f32_e32 v139, v136, v102
	ds_write_b16 v120, v150 offset:544
	s_waitcnt lgkmcnt(14)
	v_lshlrev_b32_e32 v150, 16, v166
	v_med3_f32 v139, v139, s0, v210
	v_mul_f32_e32 v153, v153, v150
	v_mul_f32_e32 v135, v135, v150
	v_mul_f32_e32 v150, 0x3fb8aa3b, v139
	v_mul_f32_e32 v139, 0xbfb8aa3b, v139
	v_mul_f32_e32 v136, 0x3fb8aa3b, v136
	v_exp_f32_e32 v150, v150
	v_exp_f32_e32 v139, v139
	v_exp_f32_e32 v136, v136
	v_cvt_pk_bf16_f32 v135, v135, s0
	v_sub_f32_e32 v140, 1.0, v140
	ds_write_b16 v120, v135 offset:816
	s_waitcnt lgkmcnt(14)
	v_lshlrev_b32_e32 v135, 16, v167
	v_mul_f32_e32 v150, v150, v135
	v_mul_f32_e32 v139, v140, v139
	v_mul_f32_e32 v135, v136, v135
	v_sub_f32_e32 v136, v137, v102
	v_cvt_pk_bf16_f32 v139, v139, s0
	v_med3_f32 v136, v136, s0, v210
	ds_write_b16 v119, v139 offset:1088
	v_mul_f32_e32 v139, 0x3fb8aa3b, v136
	v_mul_f32_e32 v136, 0xbfb8aa3b, v136
	v_exp_f32_e32 v136, v136
	v_sub_f32_e32 v141, 1.0, v141
	v_mul_f32_e32 v137, 0x3fb8aa3b, v137
	v_exp_f32_e32 v139, v139
	v_exp_f32_e32 v137, v137
	v_mul_f32_e32 v136, v141, v136
	v_cvt_pk_bf16_f32 v136, v136, s0
	v_cvt_pk_bf16_f32 v135, v135, s0
	ds_write_b16 v119, v136 offset:1360
	v_sub_f32_e32 v136, v138, v102
	ds_write_b16 v120, v135 offset:1088
	s_waitcnt lgkmcnt(14)
	v_lshlrev_b32_e32 v135, 16, v168
	v_med3_f32 v136, v136, s0, v210
	v_mul_f32_e32 v139, v139, v135
	v_mul_f32_e32 v135, v137, v135
	v_mul_f32_e32 v137, 0x3fb8aa3b, v136
	v_exp_f32_e32 v137, v137
	v_cvt_pk_bf16_f32 v135, v135, s0
	v_mul_f32_e32 v136, 0xbfb8aa3b, v136
	ds_write_b16 v120, v135 offset:1360
	v_lshlrev_b32_e32 v135, 16, v169
	v_exp_f32_e32 v136, v136
	v_mul_f32_e32 v137, v137, v135
	v_cvt_pk_bf16_f32 v137, v137, s0
	v_sub_f32_e32 v142, 1.0, v142
	ds_write_b16 v108, v137 offset:53856
	v_mul_f32_e32 v137, 0x3fb8aa3b, v138
	v_exp_f32_e32 v137, v137
	v_mul_f32_e32 v136, v142, v136
	v_cvt_pk_bf16_f32 v136, v136, s0
	ds_write_b16 v119, v136 offset:1632
	v_sub_f32_e32 v136, v143, v102
	v_med3_f32 v136, v136, s0, v210
	v_mul_f32_e32 v135, v137, v135
	v_mul_f32_e32 v137, 0x3fb8aa3b, v136
	v_exp_f32_e32 v137, v137
	v_cvt_pk_bf16_f32 v135, v135, s0
	ds_write_b16 v120, v135 offset:1632
	v_lshlrev_b32_e32 v135, 16, v180
	v_mul_f32_e32 v137, v137, v135
	v_cvt_pk_bf16_f32 v137, v137, s0
	ds_write_b16 v108, v137 offset:54128
	v_mul_f32_e32 v137, 0x3fb8aa3b, v143
	v_exp_f32_e32 v137, v137
	v_mul_f32_e32 v136, 0xbfb8aa3b, v136
	v_exp_f32_e32 v136, v136
	v_sub_f32_e32 v149, 1.0, v149
	v_mul_f32_e32 v135, v137, v135
	v_cvt_pk_bf16_f32 v135, v135, s0
	v_mul_f32_e32 v136, v149, v136
	ds_write_b16 v120, v135 offset:1904
	v_sub_f32_e32 v135, v144, v102
	v_cvt_pk_bf16_f32 v136, v136, s0
	v_med3_f32 v135, v135, s0, v210
	ds_write_b16 v119, v136 offset:1904
	v_mul_f32_e32 v136, 0x3fb8aa3b, v135
	v_cvt_pk_bf16_f32 v153, v153, s0
	v_cvt_pk_bf16_f32 v150, v150, s0
	v_cvt_pk_bf16_f32 v139, v139, s0
	v_exp_f32_e32 v136, v136
	ds_write_b16 v108, v153 offset:53040
	ds_write_b16 v108, v150 offset:53312
	ds_write_b16 v108, v139 offset:53584
	ds_read_u16 v137, v108 offset:2176
	ds_read_u16 v138, v108 offset:2448
	ds_read_u16 v139, v108 offset:2720
	ds_read_u16 v140, v108 offset:2992
	ds_read_u16 v141, v108 offset:3264
	ds_read_u16 v142, v108 offset:3536
	ds_read_u16 v143, v108 offset:3808
	ds_read_u16 v149, v108 offset:4080
	s_waitcnt lgkmcnt(7)
; #define LAS __attribute__((address_space(3)))
; __device__ __forceinline__ unsigned pk2(float lo, float hi) { return pg8::cvt_pk_bf16(lo, hi); }
; __device__ __forceinline__ void hgrn3_phase(unsigned char* ws, const float* lbl, const float* nw, LAS unsigned char* lds, int tid, int lane, int wave, int G) {
;     ...
; #pragma unroll
;             for (int i = 0; i < 16; ++i) {
;                 const int t = 16 * j + i;
;                 const float q = bf2f(*(LAS const unsigned short*)(rawQ + t * RAWP + 2 * c));
;                 const float dq = fminf(fmaxf(bc[i] - bref, -80.f), 80.f);
;                 *(LAS unsigned short*)(QT + t * RAWP + 2 * c) = (unsigned short)pk2(q * __expf(dq), 0.f);
;                 *(LAS unsigned short*)(KT + t * RAWP + 2 * c) = (unsigned short)pk2(kv[i] * __expf(-dq), 0.f);
;                 *(LAS unsigned short*)(QH + t * RAWP + 2 * c) = (unsigned short)pk2(q * __expf(bc[i]), 0.f);
;             }
;             float tmp[16];
; #pragma unroll
;             for (int i = 0; i < 16; ++i) tmp[i] = bf2f(*(LAS const unsigned short*)(rawI + (16 * j + i) * RAWP + 2 * c));
;             st16bf(VT + c * KTP + j * 32, tmp);
;         }
;         __syncthreads();
	v_lshlrev_b32_e32 v137, 16, v137
	v_mul_f32_e32 v136, v136, v137
	v_mul_f32_e32 v135, 0xbfb8aa3b, v135
	v_cvt_pk_bf16_f32 v136, v136, s0
	v_exp_f32_e32 v135, v135
	ds_write_b16 v108, v136 offset:54400
	v_mul_f32_e32 v136, 0x3fb8aa3b, v144
	v_exp_f32_e32 v136, v136
	v_sub_f32_e32 v151, 1.0, v151
	v_mul_f32_e32 v135, v151, v135
	v_cvt_pk_bf16_f32 v135, v135, s0
	ds_write_b16 v119, v135 offset:2176
	v_mul_f32_e32 v135, v136, v137
	v_sub_f32_e32 v136, v145, v102
	v_med3_f32 v136, v136, s0, v210
	v_mul_f32_e32 v137, 0x3fb8aa3b, v136
	v_exp_f32_e32 v137, v137
	v_cvt_pk_bf16_f32 v135, v135, s0
	v_mul_f32_e32 v136, 0xbfb8aa3b, v136
	ds_write_b16 v120, v135 offset:2176
	s_waitcnt lgkmcnt(9)
	v_lshlrev_b32_e32 v135, 16, v138
	v_exp_f32_e32 v136, v136
	v_mul_f32_e32 v137, v137, v135
	v_cvt_pk_bf16_f32 v137, v137, s0
	v_sub_f32_e32 v154, 1.0, v154
	ds_write_b16 v108, v137 offset:54672
	v_mul_f32_e32 v137, 0x3fb8aa3b, v145
	v_exp_f32_e32 v137, v137
	v_mul_f32_e32 v136, v154, v136
	v_cvt_pk_bf16_f32 v136, v136, s0
	ds_write_b16 v119, v136 offset:2448
	v_sub_f32_e32 v136, v146, v102
	v_med3_f32 v136, v136, s0, v210
	v_mul_f32_e32 v135, v137, v135
	v_mul_f32_e32 v137, 0x3fb8aa3b, v136
	v_exp_f32_e32 v137, v137
	v_cvt_pk_bf16_f32 v135, v135, s0
	v_mul_f32_e32 v136, 0xbfb8aa3b, v136
	ds_write_b16 v120, v135 offset:2448
	s_waitcnt lgkmcnt(11)
	v_lshlrev_b32_e32 v135, 16, v139
	v_exp_f32_e32 v136, v136
	v_mul_f32_e32 v137, v137, v135
	v_cvt_pk_bf16_f32 v137, v137, s0
	v_sub_f32_e32 v155, 1.0, v155
	ds_write_b16 v108, v137 offset:54944
	v_mul_f32_e32 v137, 0x3fb8aa3b, v146
	v_exp_f32_e32 v137, v137
	v_mul_f32_e32 v136, v155, v136
	v_cvt_pk_bf16_f32 v136, v136, s0
	ds_write_b16 v119, v136 offset:2720
	v_sub_f32_e32 v136, v147, v102
	v_med3_f32 v136, v136, s0, v210
	v_mul_f32_e32 v135, v137, v135
	v_mul_f32_e32 v137, 0x3fb8aa3b, v136
	v_exp_f32_e32 v137, v137
	v_cvt_pk_bf16_f32 v135, v135, s0
	v_mul_f32_e32 v136, 0xbfb8aa3b, v136
	ds_write_b16 v120, v135 offset:2720
	s_waitcnt lgkmcnt(13)
	v_lshlrev_b32_e32 v135, 16, v140
	v_exp_f32_e32 v136, v136
	v_mul_f32_e32 v137, v137, v135
	v_cvt_pk_bf16_f32 v137, v137, s0
	v_sub_f32_e32 v156, 1.0, v156
	ds_write_b16 v108, v137 offset:55216
	v_mul_f32_e32 v137, 0x3fb8aa3b, v147
	v_exp_f32_e32 v137, v137
	v_mul_f32_e32 v136, v156, v136
	v_cvt_pk_bf16_f32 v136, v136, s0
	ds_write_b16 v119, v136 offset:2992
	v_sub_f32_e32 v136, v148, v102
	v_med3_f32 v136, v136, s0, v210
	v_mul_f32_e32 v135, v137, v135
	v_mul_f32_e32 v137, 0x3fb8aa3b, v136
	v_exp_f32_e32 v137, v137
	v_cvt_pk_bf16_f32 v135, v135, s0
	ds_write_b16 v120, v135 offset:2992
	s_waitcnt lgkmcnt(14)
	v_lshlrev_b32_e32 v135, 16, v141
	v_mul_f32_e32 v137, v137, v135
	v_mul_f32_e32 v136, 0xbfb8aa3b, v136
	v_cvt_pk_bf16_f32 v137, v137, s0
	v_exp_f32_e32 v136, v136
	ds_write_b16 v108, v137 offset:55488
	v_mul_f32_e32 v137, 0x3fb8aa3b, v148
	v_exp_f32_e32 v137, v137
	v_mul_f32_e32 v133, v133, v136
	v_cvt_pk_bf16_f32 v133, v133, s0
	ds_write_b16 v119, v133 offset:3264
	v_mul_f32_e32 v133, v137, v135
	v_sub_f32_e32 v135, v134, v102
	v_med3_f32 v135, v135, s0, v210
	v_mul_f32_e32 v136, 0x3fb8aa3b, v135
	v_mul_f32_e32 v135, 0xbfb8aa3b, v135
	v_exp_f32_e32 v135, v135
	v_mul_f32_e32 v134, 0x3fb8aa3b, v134
	v_exp_f32_e32 v136, v136
	v_exp_f32_e32 v134, v134
	v_cvt_pk_bf16_f32 v133, v133, s0
	v_mul_f32_e32 v131, v131, v135
	ds_write_b16 v120, v133 offset:3264
	v_lshlrev_b32_e32 v133, 16, v142
	v_cvt_pk_bf16_f32 v131, v131, s0
	v_mul_f32_e32 v136, v136, v133
	ds_write_b16 v119, v131 offset:3536
	v_mul_f32_e32 v131, v134, v133
	v_sub_f32_e32 v133, v132, v102
	v_med3_f32 v133, v133, s0, v210
	v_mul_f32_e32 v134, 0x3fb8aa3b, v133
	v_mul_f32_e32 v133, 0xbfb8aa3b, v133
	v_exp_f32_e32 v133, v133
	v_mul_f32_e32 v132, 0x3fb8aa3b, v132
	v_exp_f32_e32 v134, v134
	v_exp_f32_e32 v132, v132
	v_cvt_pk_bf16_f32 v131, v131, s0
	v_mul_f32_e32 v130, v130, v133
	v_sub_f32_e32 v102, v129, v102
	ds_write_b16 v120, v131 offset:3536
	s_waitcnt lgkmcnt(14)
	v_lshlrev_b32_e32 v131, 16, v143
	v_cvt_pk_bf16_f32 v130, v130, s0
	v_med3_f32 v102, v102, s0, v210
	v_mul_f32_e32 v134, v134, v131
	ds_write_b16 v119, v130 offset:3808
	v_mul_f32_e32 v130, v132, v131
	v_mul_f32_e32 v131, 0x3fb8aa3b, v102
	v_mul_f32_e32 v102, 0xbfb8aa3b, v102
	v_exp_f32_e32 v102, v102
	v_mul_f32_e32 v129, 0x3fb8aa3b, v129
	v_exp_f32_e32 v131, v131
	v_exp_f32_e32 v129, v129
	v_cvt_pk_bf16_f32 v130, v130, s0
	v_mul_f32_e32 v102, v103, v102
	ds_write_b16 v120, v130 offset:3808
	v_lshlrev_b32_e32 v130, 16, v149
	v_cvt_pk_bf16_f32 v102, v102, s0
	v_mul_f32_e32 v131, v131, v130
	ds_write_b16 v119, v102 offset:4080
	v_mul_f32_e32 v102, v129, v130
	v_cvt_pk_bf16_f32 v136, v136, s0
	v_cvt_pk_bf16_f32 v134, v134, s0
	v_cvt_pk_bf16_f32 v131, v131, s0
	v_cvt_pk_bf16_f32 v102, v102, s0
	ds_write_b16 v108, v136 offset:55760
	ds_write_b16 v108, v134 offset:56032
	ds_write_b16 v108, v131 offset:56304
	ds_write_b16 v120, v102 offset:4080
	ds_read_u16 v102, v108 offset:34816
	ds_read_u16 v103, v108 offset:35088
	ds_read_u16 v129, v108 offset:35360
	ds_read_u16 v130, v108 offset:35632
	ds_read_u16 v131, v108 offset:35904
	ds_read_u16 v132, v108 offset:36176
	ds_read_u16 v133, v108 offset:36448
	ds_read_u16 v134, v108 offset:36720
	s_waitcnt lgkmcnt(4)
	v_lshlrev_b32_e32 v135, 16, v130
	s_waitcnt lgkmcnt(3)
	v_lshlrev_b32_e32 v136, 16, v131
	ds_read_u16 v130, v108 offset:36992
	ds_read_u16 v131, v108 offset:37264
	ds_read_u16 v137, v108 offset:37536
	ds_read_u16 v138, v108 offset:37808
	ds_read_u16 v139, v108 offset:38080
	ds_read_u16 v140, v108 offset:38352
	ds_read_u16 v141, v108 offset:38624
	ds_read_u16 v142, v108 offset:38896
	v_lshlrev_b32_e32 v102, 16, v102
	v_lshlrev_b32_e32 v103, 16, v103
	v_lshlrev_b32_e32 v129, 16, v129
	s_waitcnt lgkmcnt(10)
	v_lshlrev_b32_e32 v132, 16, v132
	s_waitcnt lgkmcnt(9)
	v_lshlrev_b32_e32 v133, 16, v133
	s_waitcnt lgkmcnt(8)
	v_lshlrev_b32_e32 v134, 16, v134
	s_waitcnt lgkmcnt(7)
	v_lshlrev_b32_e32 v143, 16, v130
	s_waitcnt lgkmcnt(6)
	v_lshlrev_b32_e32 v144, 16, v131
	s_waitcnt lgkmcnt(5)
	v_lshlrev_b32_e32 v137, 16, v137
	s_waitcnt lgkmcnt(4)
	v_lshlrev_b32_e32 v138, 16, v138
	s_waitcnt lgkmcnt(3)
	v_lshlrev_b32_e32 v139, 16, v139
	s_waitcnt lgkmcnt(2)
	v_lshlrev_b32_e32 v140, 16, v140
	s_waitcnt lgkmcnt(1)
	v_lshlrev_b32_e32 v141, 16, v141
	s_waitcnt lgkmcnt(0)
	v_lshlrev_b32_e32 v142, 16, v142
	v_cvt_pk_bf16_f32 v130, v102, v103
	v_cvt_pk_bf16_f32 v131, v129, v135
	v_cvt_pk_bf16_f32 v132, v136, v132
	v_cvt_pk_bf16_f32 v133, v133, v134
	v_cvt_pk_bf16_f32 v134, v143, v144
	v_cvt_pk_bf16_f32 v135, v137, v138
	v_cvt_pk_bf16_f32 v136, v139, v140
	v_cvt_pk_bf16_f32 v137, v141, v142
	ds_write_b128 v121, v[130:133]
	ds_write_b128 v121, v[134:137] offset:16
	s_waitcnt lgkmcnt(0)
	s_barrier
; #define LAS __attribute__((address_space(3)))
; __device__ __forceinline__ void hgrn3_phase(unsigned char* ws, const float* lbl, const float* nw, LAS unsigned char* lds, int tid, int lane, int wave, int G) {
;     ...
;         {
;             bf16x8 qfr[4];
; #pragma unroll
;             for (int kk = 0; kk < 4; ++kk) qfr[kk] = *(LAS const bf16x8*)(QT + (16 * tt + fr) * RAWP + (8 * fq + 32 * kk) * 2);
; #pragma unroll
;             for (int si = 0; si < 2; ++si) {
;                 const int stile = 2 * wh + si;
;                 f32x4 cacc = (f32x4){0.f, 0.f, 0.f, 0.f};
; #pragma unroll
;                 for (int kk = 0; kk < 4; ++kk) { const bf16x8 kfr = *(LAS const bf16x8*)(KT + (16 * stile + fr) * RAWP + (8 * fq + 32 * kk) * 2);
;                     cacc = __builtin_amdgcn_mfma_f32_16x16x32_bf16(kfr, qfr[kk], cacc, 0, 0, 0); }
;                 const int t = 16 * tt + fr, s0 = 16 * stile + 4 * fq;
; #pragma unroll
;                 for (int i = 0; i < 4; ++i) cacc[i] = (s0 + i <= t) ? cacc[i] : 0.f;
;                 v2u w; w.x = pk2(cacc[0], cacc[1]); w.y = pk2(cacc[2], cacc[3]);
;                 *(LAS v2u*)(PT + t * KTP + s0 * 2) = w;
;             }
;         }
;         __syncthreads();
;         v2u gpre[4];
; #pragma unroll
;         for (int n = 0; n < 4; ++n) gpre[n] = gld<v2u>(HG + (size_t)(tok0 + 16 * tt + fr) * 512 + hh * 128 + 16 * (4 * wh + n) + 4 * fq);
;         f32x4 oacc[4];
;         {
;             bf16x8 pfr[2], qh[4];
; #pragma unroll
;             for (int kk = 0; kk < 2; ++kk) pfr[kk] = *(LAS const bf16x8*)(PT + (16 * tt + fr) * KTP + (8 * fq + 32 * kk) * 2);
; #pragma unroll
;             for (int kk = 0; kk < 4; ++kk) qh[kk] = *(LAS const bf16x8*)(QH + (16 * tt + fr) * RAWP + (8 * fq + 32 * kk) * 2);
; #pragma unroll
;             for (int n = 0; n < 4; ++n) {
;                 f32x4 cacc = (f32x4){0.f, 0.f, 0.f, 0.f};
; #pragma unroll
;                 for (int kk = 0; kk < 2; ++kk) { const bf16x8 vfr = *(LAS const bf16x8*)(VT + (16 * (4 * wh + n) + fr) * KTP + (8 * fq + 32 * kk) * 2);
;                     cacc = __builtin_amdgcn_mfma_f32_16x16x32_bf16(vfr, pfr[kk], cacc, 0, 0, 0); }
; #pragma unroll
;                 for (int kk = 0; kk < 4; ++kk) cacc = __builtin_amdgcn_mfma_f32_16x16x32_bf16(sf[n][kk], qh[kk], cacc, 0, 0, 0);
;                 oacc[n] = cacc;
;             }
;         }
;         float sq = 0.f;
; #pragma unroll
	ds_read_b128 v[130:133], v123
	ds_read_b128 v[134:137], v122 offset:52224
	ds_read_b128 v[138:141], v123 offset:64
	ds_read_b128 v[142:145], v122 offset:52288
	s_waitcnt lgkmcnt(2)
	v_mfma_f32_16x16x32_bf16 v[130:133], v[130:133], v[134:137], 0
	ds_read_b128 v[146:149], v123 offset:128
	ds_read_b128 v[150:153], v122 offset:52352
	s_and_b32 s0, s42, 0x1fc0
	s_and_b32 s1, s43, 0xffffe000
	s_waitcnt lgkmcnt(2)
	v_mfma_f32_16x16x32_bf16 v[130:133], v[138:141], v[142:145], v[130:133]
	ds_read_b128 v[138:141], v123 offset:192
	s_or_b32 s0, s1, s0
	s_and_b32 s48, s48, 0x180
	s_waitcnt lgkmcnt(1)
	v_mfma_f32_16x16x32_bf16 v[130:133], v[146:149], v[150:153], v[130:133]
	ds_read_b128 v[146:149], v122 offset:52416
	s_lshl_b32 s90, s48, 1
	s_mov_b32 s1, s91
	s_waitcnt lgkmcnt(0)
	v_mfma_f32_16x16x32_bf16 v[130:133], v[138:141], v[146:149], v[130:133]
	s_nop 7
	v_cndmask_b32_e64 v102, v130, 0, s[6:7]
	v_cndmask_b32_e64 v103, 0, v131, s[8:9]
	v_cndmask_b32_e64 v129, v132, 0, s[10:11]
	v_cndmask_b32_e64 v130, v133, 0, s[12:13]
	v_cvt_pk_bf16_f32 v102, v102, v103
	v_cvt_pk_bf16_f32 v103, v129, v130
	ds_write_b64 v124, v[102:103]
	ds_read_b128 v[130:133], v125
	s_waitcnt lgkmcnt(0)
	v_mfma_f32_16x16x32_bf16 v[130:133], v[130:133], v[134:137], 0
	ds_read_b128 v[134:137], v125 offset:64
	s_waitcnt lgkmcnt(0)
	v_mfma_f32_16x16x32_bf16 v[130:133], v[134:137], v[142:145], v[130:133]
	ds_read_b128 v[134:137], v125 offset:128
	s_waitcnt lgkmcnt(0)
	v_mfma_f32_16x16x32_bf16 v[130:133], v[134:137], v[150:153], v[130:133]
	ds_read_b128 v[134:137], v125 offset:192
	s_waitcnt lgkmcnt(0)
	v_mfma_f32_16x16x32_bf16 v[130:133], v[134:137], v[146:149], v[130:133]
	s_nop 7
	v_cndmask_b32_e64 v102, v130, 0, s[14:15]
	v_cndmask_b32_e64 v103, 0, v131, s[16:17]
	v_cndmask_b32_e64 v129, v132, 0, s[18:19]
	v_cndmask_b32_e64 v130, v133, 0, s[20:21]
	v_cvt_pk_bf16_f32 v102, v102, v103
	v_cvt_pk_bf16_f32 v103, v129, v130
	ds_write_b64 v126, v[102:103]
	s_waitcnt lgkmcnt(0)
	s_barrier
	ds_read_b128 v[130:133], v128
	v_add_u32_e32 v102, v111, v110
	ds_read_b128 v[134:137], v102
	ds_read_b128 v[138:141], v128 offset:64
	ds_read_b128 v[142:145], v102 offset:64
	ds_read_b128 v[146:149], v128 offset:2368
	s_waitcnt lgkmcnt(3)
	v_mfma_f32_16x16x32_bf16 v[130:133], v[130:133], v[134:137], 0
	s_waitcnt lgkmcnt(1)
	v_mfma_f32_16x16x32_bf16 v[130:133], v[138:141], v[142:145], v[130:133]
	ds_read_b128 v[138:141], v127
	s_waitcnt vmcnt(15) lgkmcnt(0)
	v_mfma_f32_16x16x32_bf16 v[76:79], v[76:79], v[138:141], v[130:133]
	s_nop 4
	ds_read_b128 v[130:133], v127 offset:64
	s_waitcnt vmcnt(14) lgkmcnt(0)
	v_mfma_f32_16x16x32_bf16 v[72:75], v[72:75], v[130:133], v[76:79]
	s_nop 2
	ds_read_b128 v[76:79], v127 offset:128
	s_waitcnt vmcnt(13) lgkmcnt(0)
	v_mfma_f32_16x16x32_bf16 v[68:71], v[68:71], v[76:79], v[72:75]
	s_nop 2
	ds_read_b128 v[72:75], v127 offset:192
	s_waitcnt vmcnt(12) lgkmcnt(0)
	v_mfma_f32_16x16x32_bf16 v[68:71], v[56:59], v[72:75], v[68:71]
	ds_read_b128 v[56:59], v128 offset:2304
	s_waitcnt lgkmcnt(0)
	v_mfma_f32_16x16x32_bf16 v[56:59], v[56:59], v[134:137], 0
	v_mfma_f32_16x16x32_bf16 v[56:59], v[146:149], v[142:145], v[56:59]
	s_waitcnt vmcnt(1)
	v_mfma_f32_16x16x32_bf16 v[56:59], v[84:87], v[138:141], v[56:59]
	v_mfma_f32_16x16x32_bf16 v[56:59], v[60:63], v[130:133], v[56:59]
	ds_read_b128 v[60:63], v128 offset:4608
	v_mfma_f32_16x16x32_bf16 v[56:59], v[64:67], v[76:79], v[56:59]
	ds_read_b128 v[64:67], v128 offset:4672
	s_waitcnt lgkmcnt(1)
	v_mfma_f32_16x16x32_bf16 v[60:63], v[60:63], v[134:137], 0
	s_waitcnt lgkmcnt(0)
	v_mfma_f32_16x16x32_bf16 v[60:63], v[64:67], v[142:145], v[60:63]
	v_mfma_f32_16x16x32_bf16 v[44:47], v[44:47], v[138:141], v[60:63]
	v_mfma_f32_16x16x32_bf16 v[44:47], v[48:51], v[130:133], v[44:47]
	ds_read_b128 v[48:51], v128 offset:6912
	v_mfma_f32_16x16x32_bf16 v[44:47], v[52:55], v[76:79], v[44:47]
	ds_read_b128 v[52:55], v128 offset:6976
	v_mfma_f32_16x16x32_bf16 v[40:43], v[40:43], v[72:75], v[44:47]
	s_waitcnt lgkmcnt(1)
	v_mfma_f32_16x16x32_bf16 v[46:49], v[48:51], v[134:137], 0
	s_nop 3
	v_add_u32_e32 v44, s0, v109
	v_ashrrev_i32_e32 v45, 31, v44
	v_lshlrev_b64 v[50:51], 10, v[44:45]
	s_waitcnt lgkmcnt(0)
	v_mfma_f32_16x16x32_bf16 v[46:49], v[52:55], v[142:145], v[46:49]
	v_lshl_add_u64 v[50:51], s[2:3], 0, v[50:51]
	v_readlane_b32 s0, v253, 17
	s_lshl_b32 s0, s0, 1
	v_mfma_f32_16x16x32_bf16 v[36:39], v[36:39], v[138:141], v[46:49]
	v_mfma_f32_16x16x32_bf16 v[32:35], v[32:35], v[130:133], v[36:39]
	s_nop 2
	v_lshl_add_u64 v[46:47], v[50:51], 0, s[90:91]
	v_lshl_add_u64 v[46:47], v[94:95], 1, v[46:47]
	v_lshl_add_u64 v[46:47], v[46:47], 0, s[0:1]
	v_mfma_f32_16x16x32_bf16 v[34:37], v[28:31], v[76:79], v[32:35]
	s_nop 0
	s_nop 1
	s_nop 0
	s_nop 0
	s_nop 0
	v_mfma_f32_16x16x32_bf16 v[56:59], v[80:83], v[72:75], v[56:59]
	s_waitcnt vmcnt(0)
	v_mfma_f32_16x16x32_bf16 v[24:27], v[24:27], v[72:75], v[34:37]
	s_nop 2
	v_mul_f32_e32 v34, v69, v69
	v_mul_f32_e32 v35, v71, v71
	v_fmac_f32_e32 v34, v68, v68
	v_fmac_f32_e32 v35, v70, v70
	v_add_f32_e32 v34, v34, v35
	v_mul_f32_e32 v35, v57, v57
	v_mul_f32_e32 v36, v59, v59
	v_fmac_f32_e32 v35, v56, v56
	v_fmac_f32_e32 v36, v58, v58
	v_add_f32_e32 v35, v35, v36
	v_add_f32_e32 v34, v34, v35
	v_mul_f32_e32 v35, v41, v41
	v_mul_f32_e32 v36, v43, v43
	v_fmac_f32_e32 v35, v40, v40
	v_fmac_f32_e32 v36, v42, v42
	v_add_f32_e32 v35, v35, v36
	v_add_f32_e32 v34, v34, v35
	v_mul_f32_e32 v35, v25, v25
	v_mul_f32_e32 v36, v27, v27
	v_fmac_f32_e32 v35, v24, v24
	v_fmac_f32_e32 v36, v26, v26
	v_add_f32_e32 v35, v35, v36
	v_add_f32_e32 v34, v34, v35
	ds_bpermute_b32 v35, v112, v34
	s_waitcnt lgkmcnt(0)
	v_add_f32_e32 v34, v34, v35
	ds_bpermute_b32 v35, v113, v34
	s_and_saveexec_b64 s[0:1], s[4:5]
	s_cbranch_execz .LBB0_23
	s_waitcnt lgkmcnt(0)
	v_add_f32_e32 v34, v34, v35
	ds_write_b32 v114, v34
	s_branch .LBB0_23
